# v21: v16 + grid barrier: each workgroup does buffer_wbl2 before its arrival atomic; the XCD's last arriver no longer flushes (drain dirty L2 lines off the critical path)
# baseline (speedup 1.0000x reference)
; __device__ __forceinline__ unsigned xb_ld(unsigned* p)              { return __hip_atomic_load(p, __ATOMIC_RELAXED, __HIP_MEMORY_SCOPE_AGENT); }
; __device__ __forceinline__ unsigned xb_add(unsigned* p, unsigned v) { return __hip_atomic_fetch_add(p, v, __ATOMIC_RELAXED, __HIP_MEMORY_SCOPE_AGENT); }
; #define XB_SPIN(cond, bar) do { unsigned _sp = 0; while (cond) { __builtin_amdgcn_s_sleep(1); \
;     if ((++_sp & 255u) == 0u) { if (xb_ld(&(bar)[XB_TMO])) break; if (_sp > XB_SPIN_CAP) { atomicAdd(&(bar)[XB_TMO], 1u); break; } } } } while (0)
; __device__ __forceinline__ void xcd_barrier(const XcdBarrier& b) {
;     ...
;         const unsigned old = xb_add(&bar[XB_XSUB(b.x)], 1u);
;         const unsigned gen = old / nloc;
;         if (old + 1u == (gen + 1u) * nloc) {
;             __builtin_amdgcn_fence(__ATOMIC_RELEASE, "agent");
;             asm volatile("s_waitcnt vmcnt(0)" ::: "memory");
;             const unsigned og = xb_add(&bar[XB_TOP], 1u);
;             const unsigned tg = og / nx;
;             if (og + 1u == (tg + 1u) * nx) xb_add(&bar[XB_TOPGEN], 1u);
;             else XB_SPIN(xb_ld(&bar[XB_TOPGEN]) == tg, bar);
;             __builtin_amdgcn_fence(__ATOMIC_ACQUIRE, "agent");
;             xb_add(&bar[XB_XGEN(b.x)], 1u);
;             asm volatile("s_waitcnt vmcnt(0)" ::: "memory");
;         } else {
;             XB_SPIN(xb_ld(&bar[XB_XGEN(b.x)]) == gen, bar);
.LBB0_120:
	s_lshl_b32 s24, s33, 6
	s_add_i32 s6, s24, 0x500
	s_mov_b32 s7, 0
	s_lshl_b64 s[4:5], s[6:7], 2
	s_add_u32 s4, s0, s4
	s_addc_u32 s5, s1, s5
	v_mov_b32_e32 v1, 1
	v_mov_b64_e32 v[4:5], s[4:5]
	buffer_wbl2 sc1
	s_waitcnt vmcnt(0)
	flat_atomic_add v1, v[4:5], v1 sc0
	v_cvt_f32_u32_e32 v3, v2
	v_sub_u32_e32 v4, 0, v2
	v_rcp_iflag_f32_e32 v3, v3
	s_nop 0
	v_mul_f32_e32 v3, 0x4f7ffffe, v3
	v_cvt_u32_f32_e32 v3, v3
	v_mul_lo_u32 v4, v4, v3
	v_mul_hi_u32 v4, v3, v4
	v_add_u32_e32 v3, v3, v4
	s_waitcnt vmcnt(0) lgkmcnt(0)
	v_mul_hi_u32 v3, v1, v3
	v_mul_lo_u32 v5, v3, v2
	v_add_u32_e32 v4, 1, v1
	v_sub_u32_e32 v1, v1, v5
	v_add_u32_e32 v6, 1, v3
	v_cmp_ge_u32_e32 vcc, v1, v2
	v_sub_u32_e32 v5, v1, v2
	s_nop 0
	v_cndmask_b32_e32 v3, v3, v6, vcc
	v_cndmask_b32_e32 v1, v1, v5, vcc
	v_add_u32_e32 v5, 1, v3
	v_cmp_ge_u32_e32 vcc, v1, v2
	s_nop 1
	v_cndmask_b32_e32 v1, v3, v5, vcc
	v_mad_u64_u32 v[2:3], s[4:5], v2, v1, v[2:3]
	v_cmp_ne_u32_e32 vcc, v4, v2
	s_and_saveexec_b64 s[4:5], vcc
	s_xor_b64 s[4:5], exec, s[4:5]
	s_cbranch_execz .LBB0_133
	s_add_i32 s6, s24, 0x900
	s_lshl_b64 s[6:7], s[6:7], 2
	s_add_u32 s8, s0, s6
	s_addc_u32 s9, s1, s7
	v_mov_b64_e32 v[2:3], s[8:9]
	flat_load_dword v0, v[2:3] sc1
	s_waitcnt vmcnt(0) lgkmcnt(0)
	v_cmp_eq_u32_e32 vcc, v0, v1
	s_and_saveexec_b64 s[6:7], vcc
	s_cbranch_execz .LBB0_132
	s_mov_b32 s25, 1
	s_mov_b64 s[10:11], 0
	s_branch .LBB0_124

; __device__ __forceinline__ unsigned xb_ld(unsigned* p)              { return __hip_atomic_load(p, __ATOMIC_RELAXED, __HIP_MEMORY_SCOPE_AGENT); }
; __device__ __forceinline__ unsigned xb_add(unsigned* p, unsigned v) { return __hip_atomic_fetch_add(p, v, __ATOMIC_RELAXED, __HIP_MEMORY_SCOPE_AGENT); }
; #define XB_SPIN(cond, bar) do { unsigned _sp = 0; while (cond) { __builtin_amdgcn_s_sleep(1); \
;     if ((++_sp & 255u) == 0u) { if (xb_ld(&(bar)[XB_TMO])) break; if (_sp > XB_SPIN_CAP) { atomicAdd(&(bar)[XB_TMO], 1u); break; } } } } while (0)
; __device__ __forceinline__ void xcd_barrier(const XcdBarrier& b) {
;     ...
;             __builtin_amdgcn_fence(__ATOMIC_RELEASE, "agent");
;             asm volatile("s_waitcnt vmcnt(0)" ::: "memory");
;             const unsigned og = xb_add(&bar[XB_TOP], 1u);
;             const unsigned tg = og / nx;
;             if (og + 1u == (tg + 1u) * nx) xb_add(&bar[XB_TOPGEN], 1u);
;             else XB_SPIN(xb_ld(&bar[XB_TOPGEN]) == tg, bar);
.LBB0_133:
	s_andn2_saveexec_b64 s[4:5], s[4:5]
	s_cbranch_execz .LBB0_149
	v_mov_b32_e32 v1, s0
	v_add_co_u32_e32 v2, vcc, 0x3000, v1
	v_mov_b32_e32 v1, s1
	s_nop 1
	v_addc_co_u32_e32 v3, vcc, 0, v1, vcc
	v_mov_b32_e32 v1, 1
	flat_atomic_add v1, v[2:3], v1 offset:1024 sc0
	v_cvt_f32_u32_e32 v2, v0
	v_sub_u32_e32 v3, 0, v0
	s_add_u32 s4, s0, 0x3500
	s_addc_u32 s5, s1, 0
	v_rcp_iflag_f32_e32 v2, v2
	s_mov_b64 s[8:9], -1
	v_mul_f32_e32 v2, 0x4f7ffffe, v2
	v_cvt_u32_f32_e32 v2, v2
	v_mul_lo_u32 v3, v3, v2
	v_mul_hi_u32 v3, v2, v3
	v_add_u32_e32 v2, v2, v3
	s_waitcnt vmcnt(0) lgkmcnt(0)
	v_mul_hi_u32 v2, v1, v2
	v_mul_lo_u32 v4, v2, v0
	v_add_u32_e32 v3, 1, v1
	v_sub_u32_e32 v1, v1, v4
	v_add_u32_e32 v5, 1, v2
	v_cmp_ge_u32_e32 vcc, v1, v0
	v_sub_u32_e32 v4, v1, v0
	s_nop 0
	v_cndmask_b32_e32 v2, v2, v5, vcc
	v_cndmask_b32_e32 v1, v1, v4, vcc
	v_add_u32_e32 v4, 1, v2
	v_cmp_ge_u32_e32 vcc, v1, v0
	s_nop 1
	v_cndmask_b32_e32 v2, v2, v4, vcc
	v_mad_u64_u32 v[0:1], s[6:7], v0, v2, v[0:1]
	v_cmp_ne_u32_e32 vcc, v3, v0
	v_mov_b64_e32 v[0:1], s[4:5]
	s_and_saveexec_b64 s[6:7], vcc
	s_cbranch_execz .LBB0_146
	v_mov_b64_e32 v[0:1], s[4:5]
	flat_load_dword v0, v[0:1] sc1
	s_mov_b64 s[12:13], 0
	s_waitcnt vmcnt(0) lgkmcnt(0)
	v_cmp_eq_u32_e32 vcc, v0, v2
	s_and_saveexec_b64 s[10:11], vcc
	s_cbranch_execz .LBB0_145
	s_add_u32 s8, s0, 0x200
	s_addc_u32 s9, s1, 0
	s_mov_b32 s25, 1
	s_branch .LBB0_138

; __device__ __forceinline__ unsigned xb_ld(unsigned* p)              { return __hip_atomic_load(p, __ATOMIC_RELAXED, __HIP_MEMORY_SCOPE_AGENT); }
; __device__ __forceinline__ unsigned xb_add(unsigned* p, unsigned v) { return __hip_atomic_fetch_add(p, v, __ATOMIC_RELAXED, __HIP_MEMORY_SCOPE_AGENT); }
; #define XB_SPIN(cond, bar) do { unsigned _sp = 0; while (cond) { __builtin_amdgcn_s_sleep(1); \
;     if ((++_sp & 255u) == 0u) { if (xb_ld(&(bar)[XB_TMO])) break; if (_sp > XB_SPIN_CAP) { atomicAdd(&(bar)[XB_TMO], 1u); break; } } } } while (0)
; __device__ __forceinline__ void xcd_barrier(const XcdBarrier& b) {
;     ...
;         const unsigned old = xb_add(&bar[XB_XSUB(b.x)], 1u);
;         const unsigned gen = old / nloc;
;         if (old + 1u == (gen + 1u) * nloc) {
;             __builtin_amdgcn_fence(__ATOMIC_RELEASE, "agent");
;             asm volatile("s_waitcnt vmcnt(0)" ::: "memory");
;             const unsigned og = xb_add(&bar[XB_TOP], 1u);
;             const unsigned tg = og / nx;
;             if (og + 1u == (tg + 1u) * nx) xb_add(&bar[XB_TOPGEN], 1u);
;             else XB_SPIN(xb_ld(&bar[XB_TOPGEN]) == tg, bar);
;             __builtin_amdgcn_fence(__ATOMIC_ACQUIRE, "agent");
;             xb_add(&bar[XB_XGEN(b.x)], 1u);
;             asm volatile("s_waitcnt vmcnt(0)" ::: "memory");
;         } else {
;             XB_SPIN(xb_ld(&bar[XB_XGEN(b.x)]) == gen, bar);
.LBB0_240:
	s_lshl_b32 s26, s44, 6
	s_add_i32 s84, s26, 0x500
	s_lshl_b64 s[6:7], s[84:85], 2
	s_add_u32 s6, s4, s6
	s_addc_u32 s7, s5, s7
	v_mov_b64_e32 v[4:5], s[6:7]
	v_mov_b32_e32 v3, 1
	buffer_wbl2 sc1
	s_waitcnt vmcnt(0)
	flat_atomic_add v4, v[4:5], v3 sc0
	v_cvt_f32_u32_e32 v3, v2
	v_sub_u32_e32 v5, 0, v2
	v_rcp_iflag_f32_e32 v3, v3
	s_nop 0
	v_mul_f32_e32 v3, 0x4f7ffffe, v3
	v_cvt_u32_f32_e32 v3, v3
	v_mul_lo_u32 v5, v5, v3
	v_mul_hi_u32 v5, v3, v5
	v_add_u32_e32 v3, v3, v5
	s_waitcnt vmcnt(0) lgkmcnt(0)
	v_mul_hi_u32 v3, v4, v3
	v_mul_lo_u32 v5, v3, v2
	v_sub_u32_e32 v5, v4, v5
	v_cmp_ge_u32_e32 vcc, v5, v2
	v_add_u32_e32 v6, 1, v3
	s_nop 0
	v_cndmask_b32_e32 v3, v3, v6, vcc
	v_sub_u32_e32 v6, v5, v2
	v_cndmask_b32_e32 v5, v5, v6, vcc
	v_cmp_ge_u32_e32 vcc, v5, v2
	v_add_u32_e32 v5, 1, v3
	v_add_u32_e32 v6, 1, v4
	v_cndmask_b32_e32 v3, v3, v5, vcc
	v_mad_u64_u32 v[4:5], s[6:7], v2, v3, v[2:3]
	v_cmp_ne_u32_e32 vcc, v6, v4
	s_and_saveexec_b64 s[6:7], vcc
	s_xor_b64 s[6:7], exec, s[6:7]
	s_cbranch_execz .LBB0_253
	s_add_i32 s84, s26, 0x900
	s_lshl_b64 s[8:9], s[84:85], 2
	s_add_u32 s10, s4, s8
	s_addc_u32 s11, s5, s9
	v_mov_b64_e32 v[4:5], s[10:11]
	flat_load_dword v0, v[4:5] sc1
	s_waitcnt vmcnt(0) lgkmcnt(0)
	v_cmp_eq_u32_e32 vcc, v0, v3
	s_and_saveexec_b64 s[8:9], vcc
	s_cbranch_execz .LBB0_252
	s_mov_b32 s27, 1
	s_mov_b64 s[12:13], 0
	s_branch .LBB0_244

; __device__ __forceinline__ unsigned xb_ld(unsigned* p)              { return __hip_atomic_load(p, __ATOMIC_RELAXED, __HIP_MEMORY_SCOPE_AGENT); }
; __device__ __forceinline__ unsigned xb_add(unsigned* p, unsigned v) { return __hip_atomic_fetch_add(p, v, __ATOMIC_RELAXED, __HIP_MEMORY_SCOPE_AGENT); }
; #define XB_SPIN(cond, bar) do { unsigned _sp = 0; while (cond) { __builtin_amdgcn_s_sleep(1); \
;     if ((++_sp & 255u) == 0u) { if (xb_ld(&(bar)[XB_TMO])) break; if (_sp > XB_SPIN_CAP) { atomicAdd(&(bar)[XB_TMO], 1u); break; } } } } while (0)
; __device__ __forceinline__ void xcd_barrier(const XcdBarrier& b) {
;     ...
;             __builtin_amdgcn_fence(__ATOMIC_RELEASE, "agent");
;             asm volatile("s_waitcnt vmcnt(0)" ::: "memory");
;             const unsigned og = xb_add(&bar[XB_TOP], 1u);
;             const unsigned tg = og / nx;
;             if (og + 1u == (tg + 1u) * nx) xb_add(&bar[XB_TOPGEN], 1u);
;             else XB_SPIN(xb_ld(&bar[XB_TOPGEN]) == tg, bar);
.LBB0_253:
	s_andn2_saveexec_b64 s[6:7], s[6:7]
	s_cbranch_execz .LBB0_269
	v_mov_b32_e32 v2, s4
	v_add_co_u32_e32 v2, vcc, 0x3000, v2
	v_mov_b32_e32 v3, s5
	s_nop 1
	v_addc_co_u32_e32 v3, vcc, 0, v3, vcc
	v_mov_b32_e32 v4, 1
	flat_atomic_add v2, v[2:3], v4 offset:1024 sc0
	v_cvt_f32_u32_e32 v3, v0
	v_sub_u32_e32 v4, 0, v0
	s_mov_b64 s[10:11], -1
	v_rcp_iflag_f32_e32 v3, v3
	s_nop 0
	v_mul_f32_e32 v3, 0x4f7ffffe, v3
	v_cvt_u32_f32_e32 v3, v3
	v_mul_lo_u32 v4, v4, v3
	v_mul_hi_u32 v4, v3, v4
	v_add_u32_e32 v3, v3, v4
	s_waitcnt vmcnt(0) lgkmcnt(0)
	v_mul_hi_u32 v3, v2, v3
	v_mul_lo_u32 v4, v3, v0
	v_sub_u32_e32 v4, v2, v4
	v_cmp_ge_u32_e32 vcc, v4, v0
	v_add_u32_e32 v5, 1, v3
	s_nop 0
	v_cndmask_b32_e32 v3, v3, v5, vcc
	v_sub_u32_e32 v5, v4, v0
	v_cndmask_b32_e32 v4, v4, v5, vcc
	v_cmp_ge_u32_e32 vcc, v4, v0
	v_add_u32_e32 v4, 1, v3
	v_add_u32_e32 v5, 1, v2
	v_cndmask_b32_e32 v4, v3, v4, vcc
	v_mad_u64_u32 v[2:3], s[6:7], v0, v4, v[0:1]
	s_add_u32 s6, s4, 0x3500
	s_addc_u32 s7, s5, 0
	v_cmp_ne_u32_e32 vcc, v5, v2
	v_mov_b64_e32 v[2:3], s[6:7]
	s_and_saveexec_b64 s[8:9], vcc
	s_cbranch_execz .LBB0_266
	v_mov_b64_e32 v[2:3], s[6:7]
	flat_load_dword v0, v[2:3] sc1
	s_mov_b64 s[14:15], 0
	s_waitcnt vmcnt(0) lgkmcnt(0)
	v_cmp_eq_u32_e32 vcc, v0, v4
	s_and_saveexec_b64 s[12:13], vcc
	s_cbranch_execz .LBB0_265
	s_add_u32 s10, s4, 0x200
	s_addc_u32 s11, s5, 0
	s_mov_b32 s27, 1
	s_branch .LBB0_258

; __device__ __forceinline__ unsigned xb_ld(unsigned* p)              { return __hip_atomic_load(p, __ATOMIC_RELAXED, __HIP_MEMORY_SCOPE_AGENT); }
; __device__ __forceinline__ unsigned xb_add(unsigned* p, unsigned v) { return __hip_atomic_fetch_add(p, v, __ATOMIC_RELAXED, __HIP_MEMORY_SCOPE_AGENT); }
; #define XB_SPIN(cond, bar) do { unsigned _sp = 0; while (cond) { __builtin_amdgcn_s_sleep(1); \
;     if ((++_sp & 255u) == 0u) { if (xb_ld(&(bar)[XB_TMO])) break; if (_sp > XB_SPIN_CAP) { atomicAdd(&(bar)[XB_TMO], 1u); break; } } } } while (0)
; __device__ __forceinline__ void xcd_barrier(const XcdBarrier& b) {
;     ...
;         const unsigned old = xb_add(&bar[XB_XSUB(b.x)], 1u);
;         const unsigned gen = old / nloc;
;         if (old + 1u == (gen + 1u) * nloc) {
;             __builtin_amdgcn_fence(__ATOMIC_RELEASE, "agent");
;             asm volatile("s_waitcnt vmcnt(0)" ::: "memory");
;             const unsigned og = xb_add(&bar[XB_TOP], 1u);
;             const unsigned tg = og / nx;
;             if (og + 1u == (tg + 1u) * nx) xb_add(&bar[XB_TOPGEN], 1u);
;             else XB_SPIN(xb_ld(&bar[XB_TOPGEN]) == tg, bar);
;             __builtin_amdgcn_fence(__ATOMIC_ACQUIRE, "agent");
;             xb_add(&bar[XB_XGEN(b.x)], 1u);
;             asm volatile("s_waitcnt vmcnt(0)" ::: "memory");
;         } else {
;             XB_SPIN(xb_ld(&bar[XB_XGEN(b.x)]) == gen, bar);
.LBB0_475:
	s_lshl_b32 s7, s7, 6
	s_add_i32 s84, s7, 0x500
	s_lshl_b64 s[8:9], s[84:85], 2
	s_add_u32 s8, s48, s8
	s_addc_u32 s9, s49, s9
	v_mov_b64_e32 v[4:5], s[8:9]
	v_mov_b32_e32 v3, 1
	buffer_wbl2 sc1
	s_waitcnt vmcnt(0)
	flat_atomic_add v4, v[4:5], v3 sc0
	v_cvt_f32_u32_e32 v3, v2
	v_sub_u32_e32 v5, 0, v2
	v_rcp_iflag_f32_e32 v3, v3
	s_nop 0
	v_mul_f32_e32 v3, 0x4f7ffffe, v3
	v_cvt_u32_f32_e32 v3, v3
	v_mul_lo_u32 v5, v5, v3
	v_mul_hi_u32 v5, v3, v5
	v_add_u32_e32 v3, v3, v5
	s_waitcnt vmcnt(0) lgkmcnt(0)
	v_mul_hi_u32 v3, v4, v3
	v_mul_lo_u32 v5, v3, v2
	v_sub_u32_e32 v5, v4, v5
	v_cmp_ge_u32_e32 vcc, v5, v2
	v_add_u32_e32 v6, 1, v3
	s_nop 0
	v_cndmask_b32_e32 v3, v3, v6, vcc
	v_sub_u32_e32 v6, v5, v2
	v_cndmask_b32_e32 v5, v5, v6, vcc
	v_cmp_ge_u32_e32 vcc, v5, v2
	v_add_u32_e32 v5, 1, v3
	v_add_u32_e32 v6, 1, v4
	v_cndmask_b32_e32 v3, v3, v5, vcc
	v_mad_u64_u32 v[4:5], s[8:9], v2, v3, v[2:3]
	v_cmp_ne_u32_e32 vcc, v6, v4
	s_and_saveexec_b64 s[8:9], vcc
	s_xor_b64 s[8:9], exec, s[8:9]
	s_cbranch_execz .LBB0_488
	s_add_i32 s84, s7, 0x900
	s_lshl_b64 s[10:11], s[84:85], 2
	s_add_u32 s12, s48, s10
	s_addc_u32 s13, s49, s11
	v_mov_b64_e32 v[4:5], s[12:13]
	flat_load_dword v0, v[4:5] sc1
	s_waitcnt vmcnt(0) lgkmcnt(0)
	v_cmp_eq_u32_e32 vcc, v0, v3
	s_and_saveexec_b64 s[10:11], vcc
	s_cbranch_execz .LBB0_487
	s_mov_b32 s28, 1
	s_mov_b64 s[14:15], 0
	s_branch .LBB0_479

; __device__ __forceinline__ unsigned xb_ld(unsigned* p)              { return __hip_atomic_load(p, __ATOMIC_RELAXED, __HIP_MEMORY_SCOPE_AGENT); }
; __device__ __forceinline__ unsigned xb_add(unsigned* p, unsigned v) { return __hip_atomic_fetch_add(p, v, __ATOMIC_RELAXED, __HIP_MEMORY_SCOPE_AGENT); }
; #define XB_SPIN(cond, bar) do { unsigned _sp = 0; while (cond) { __builtin_amdgcn_s_sleep(1); \
;     if ((++_sp & 255u) == 0u) { if (xb_ld(&(bar)[XB_TMO])) break; if (_sp > XB_SPIN_CAP) { atomicAdd(&(bar)[XB_TMO], 1u); break; } } } } while (0)
; __device__ __forceinline__ void xcd_barrier(const XcdBarrier& b) {
;     ...
;             __builtin_amdgcn_fence(__ATOMIC_RELEASE, "agent");
;             asm volatile("s_waitcnt vmcnt(0)" ::: "memory");
;             const unsigned og = xb_add(&bar[XB_TOP], 1u);
;             const unsigned tg = og / nx;
;             if (og + 1u == (tg + 1u) * nx) xb_add(&bar[XB_TOPGEN], 1u);
;             else XB_SPIN(xb_ld(&bar[XB_TOPGEN]) == tg, bar);
.LBB0_488:
	s_andn2_saveexec_b64 s[8:9], s[8:9]
	s_cbranch_execz .LBB0_504
	v_mov_b32_e32 v2, s48
	v_add_co_u32_e32 v2, vcc, 0x3000, v2
	v_mov_b32_e32 v3, s49
	s_nop 1
	v_addc_co_u32_e32 v3, vcc, 0, v3, vcc
	v_mov_b32_e32 v4, 1
	flat_atomic_add v2, v[2:3], v4 offset:1024 sc0
	v_cvt_f32_u32_e32 v3, v0
	v_sub_u32_e32 v4, 0, v0
	s_mov_b64 s[12:13], -1
	v_rcp_iflag_f32_e32 v3, v3
	s_nop 0
	v_mul_f32_e32 v3, 0x4f7ffffe, v3
	v_cvt_u32_f32_e32 v3, v3
	v_mul_lo_u32 v4, v4, v3
	v_mul_hi_u32 v4, v3, v4
	v_add_u32_e32 v3, v3, v4
	s_waitcnt vmcnt(0) lgkmcnt(0)
	v_mul_hi_u32 v3, v2, v3
	v_mul_lo_u32 v4, v3, v0
	v_sub_u32_e32 v4, v2, v4
	v_cmp_ge_u32_e32 vcc, v4, v0
	v_add_u32_e32 v5, 1, v3
	s_nop 0
	v_cndmask_b32_e32 v3, v3, v5, vcc
	v_sub_u32_e32 v5, v4, v0
	v_cndmask_b32_e32 v4, v4, v5, vcc
	v_cmp_ge_u32_e32 vcc, v4, v0
	v_add_u32_e32 v4, 1, v3
	v_add_u32_e32 v5, 1, v2
	v_cndmask_b32_e32 v4, v3, v4, vcc
	v_mad_u64_u32 v[2:3], s[8:9], v0, v4, v[0:1]
	s_add_u32 s8, s48, 0x3500
	s_addc_u32 s9, s49, 0
	v_cmp_ne_u32_e32 vcc, v5, v2
	v_mov_b64_e32 v[2:3], s[8:9]
	s_and_saveexec_b64 s[10:11], vcc
	s_cbranch_execz .LBB0_501
	v_mov_b64_e32 v[2:3], s[8:9]
	flat_load_dword v0, v[2:3] sc1
	s_mov_b64 s[16:17], 0
	s_waitcnt vmcnt(0) lgkmcnt(0)
	v_cmp_eq_u32_e32 vcc, v0, v4
	s_and_saveexec_b64 s[14:15], vcc
	s_cbranch_execz .LBB0_500
	s_add_u32 s12, s48, 0x200
	s_addc_u32 s13, s49, 0
	s_mov_b32 s28, 1
	s_branch .LBB0_493

; __device__ __forceinline__ unsigned xb_ld(unsigned* p)              { return __hip_atomic_load(p, __ATOMIC_RELAXED, __HIP_MEMORY_SCOPE_AGENT); }
; __device__ __forceinline__ unsigned xb_add(unsigned* p, unsigned v) { return __hip_atomic_fetch_add(p, v, __ATOMIC_RELAXED, __HIP_MEMORY_SCOPE_AGENT); }
; #define XB_SPIN(cond, bar) do { unsigned _sp = 0; while (cond) { __builtin_amdgcn_s_sleep(1); \
;     if ((++_sp & 255u) == 0u) { if (xb_ld(&(bar)[XB_TMO])) break; if (_sp > XB_SPIN_CAP) { atomicAdd(&(bar)[XB_TMO], 1u); break; } } } } while (0)
; __device__ __forceinline__ void xcd_barrier(const XcdBarrier& b) {
;     ...
;         const unsigned old = xb_add(&bar[XB_XSUB(b.x)], 1u);
;         const unsigned gen = old / nloc;
;         if (old + 1u == (gen + 1u) * nloc) {
;             __builtin_amdgcn_fence(__ATOMIC_RELEASE, "agent");
;             asm volatile("s_waitcnt vmcnt(0)" ::: "memory");
;             const unsigned og = xb_add(&bar[XB_TOP], 1u);
;             const unsigned tg = og / nx;
;             if (og + 1u == (tg + 1u) * nx) xb_add(&bar[XB_TOPGEN], 1u);
;             else XB_SPIN(xb_ld(&bar[XB_TOPGEN]) == tg, bar);
;             __builtin_amdgcn_fence(__ATOMIC_ACQUIRE, "agent");
;             xb_add(&bar[XB_XGEN(b.x)], 1u);
;             asm volatile("s_waitcnt vmcnt(0)" ::: "memory");
;         } else {
;             XB_SPIN(xb_ld(&bar[XB_XGEN(b.x)]) == gen, bar);
.LBB0_599:
	s_lshl_b32 s6, s6, 6
	s_add_i32 s84, s6, 0x500
	s_lshl_b64 s[8:9], s[84:85], 2
	s_add_u32 s8, s48, s8
	s_addc_u32 s9, s49, s9
	v_mov_b64_e32 v[4:5], s[8:9]
	v_mov_b32_e32 v3, 1
	buffer_wbl2 sc1
	s_waitcnt vmcnt(0)
	flat_atomic_add v4, v[4:5], v3 sc0
	v_cvt_f32_u32_e32 v3, v2
	v_sub_u32_e32 v5, 0, v2
	v_rcp_iflag_f32_e32 v3, v3
	s_nop 0
	v_mul_f32_e32 v3, 0x4f7ffffe, v3
	v_cvt_u32_f32_e32 v3, v3
	v_mul_lo_u32 v5, v5, v3
	v_mul_hi_u32 v5, v3, v5
	v_add_u32_e32 v3, v3, v5
	s_waitcnt vmcnt(0) lgkmcnt(0)
	v_mul_hi_u32 v3, v4, v3
	v_mul_lo_u32 v5, v3, v2
	v_sub_u32_e32 v5, v4, v5
	v_cmp_ge_u32_e32 vcc, v5, v2
	v_add_u32_e32 v6, 1, v3
	s_nop 0
	v_cndmask_b32_e32 v3, v3, v6, vcc
	v_sub_u32_e32 v6, v5, v2
	v_cndmask_b32_e32 v5, v5, v6, vcc
	v_cmp_ge_u32_e32 vcc, v5, v2
	v_add_u32_e32 v5, 1, v3
	v_add_u32_e32 v6, 1, v4
	v_cndmask_b32_e32 v3, v3, v5, vcc
	v_mad_u64_u32 v[4:5], s[8:9], v2, v3, v[2:3]
	v_cmp_ne_u32_e32 vcc, v6, v4
	s_and_saveexec_b64 s[8:9], vcc
	s_xor_b64 s[8:9], exec, s[8:9]
	s_cbranch_execz .LBB0_612
	s_add_i32 s84, s6, 0x900
	s_lshl_b64 s[10:11], s[84:85], 2
	s_add_u32 s12, s48, s10
	s_addc_u32 s13, s49, s11
	v_mov_b64_e32 v[4:5], s[12:13]
	flat_load_dword v0, v[4:5] sc1
	s_waitcnt vmcnt(0) lgkmcnt(0)
	v_cmp_eq_u32_e32 vcc, v0, v3
	s_and_saveexec_b64 s[10:11], vcc
	s_cbranch_execz .LBB0_611
	s_mov_b32 s7, 1
	s_mov_b64 s[14:15], 0
	s_branch .LBB0_603

; __device__ __forceinline__ unsigned xb_ld(unsigned* p)              { return __hip_atomic_load(p, __ATOMIC_RELAXED, __HIP_MEMORY_SCOPE_AGENT); }
; __device__ __forceinline__ unsigned xb_add(unsigned* p, unsigned v) { return __hip_atomic_fetch_add(p, v, __ATOMIC_RELAXED, __HIP_MEMORY_SCOPE_AGENT); }
; #define XB_SPIN(cond, bar) do { unsigned _sp = 0; while (cond) { __builtin_amdgcn_s_sleep(1); \
;     if ((++_sp & 255u) == 0u) { if (xb_ld(&(bar)[XB_TMO])) break; if (_sp > XB_SPIN_CAP) { atomicAdd(&(bar)[XB_TMO], 1u); break; } } } } while (0)
; __device__ __forceinline__ void xcd_barrier(const XcdBarrier& b) {
;     ...
;             __builtin_amdgcn_fence(__ATOMIC_RELEASE, "agent");
;             asm volatile("s_waitcnt vmcnt(0)" ::: "memory");
;             const unsigned og = xb_add(&bar[XB_TOP], 1u);
;             const unsigned tg = og / nx;
;             if (og + 1u == (tg + 1u) * nx) xb_add(&bar[XB_TOPGEN], 1u);
;             else XB_SPIN(xb_ld(&bar[XB_TOPGEN]) == tg, bar);
.LBB0_612:
	s_andn2_saveexec_b64 s[8:9], s[8:9]
	s_cbranch_execz .LBB0_628
	v_mov_b32_e32 v2, s48
	v_add_co_u32_e32 v2, vcc, 0x3000, v2
	v_mov_b32_e32 v3, s49
	s_nop 1
	v_addc_co_u32_e32 v3, vcc, 0, v3, vcc
	v_mov_b32_e32 v4, 1
	flat_atomic_add v2, v[2:3], v4 offset:1024 sc0
	v_cvt_f32_u32_e32 v3, v0
	v_sub_u32_e32 v4, 0, v0
	s_mov_b64 s[12:13], -1
	v_rcp_iflag_f32_e32 v3, v3
	s_nop 0
	v_mul_f32_e32 v3, 0x4f7ffffe, v3
	v_cvt_u32_f32_e32 v3, v3
	v_mul_lo_u32 v4, v4, v3
	v_mul_hi_u32 v4, v3, v4
	v_add_u32_e32 v3, v3, v4
	s_waitcnt vmcnt(0) lgkmcnt(0)
	v_mul_hi_u32 v3, v2, v3
	v_mul_lo_u32 v4, v3, v0
	v_sub_u32_e32 v4, v2, v4
	v_cmp_ge_u32_e32 vcc, v4, v0
	v_add_u32_e32 v5, 1, v3
	s_nop 0
	v_cndmask_b32_e32 v3, v3, v5, vcc
	v_sub_u32_e32 v5, v4, v0
	v_cndmask_b32_e32 v4, v4, v5, vcc
	v_cmp_ge_u32_e32 vcc, v4, v0
	v_add_u32_e32 v4, 1, v3
	v_add_u32_e32 v5, 1, v2
	v_cndmask_b32_e32 v4, v3, v4, vcc
	v_mad_u64_u32 v[2:3], s[8:9], v0, v4, v[0:1]
	s_add_u32 s8, s48, 0x3500
	s_addc_u32 s9, s49, 0
	v_cmp_ne_u32_e32 vcc, v5, v2
	v_mov_b64_e32 v[2:3], s[8:9]
	s_and_saveexec_b64 s[10:11], vcc
	s_cbranch_execz .LBB0_625
	v_mov_b64_e32 v[2:3], s[8:9]
	flat_load_dword v0, v[2:3] sc1
	s_mov_b64 s[16:17], 0
	s_waitcnt vmcnt(0) lgkmcnt(0)
	v_cmp_eq_u32_e32 vcc, v0, v4
	s_and_saveexec_b64 s[14:15], vcc
	s_cbranch_execz .LBB0_624
	s_add_u32 s12, s48, 0x200
	s_addc_u32 s13, s49, 0
	s_mov_b32 s7, 1
	s_branch .LBB0_617

; __device__ __forceinline__ unsigned xb_ld(unsigned* p)              { return __hip_atomic_load(p, __ATOMIC_RELAXED, __HIP_MEMORY_SCOPE_AGENT); }
; __device__ __forceinline__ unsigned xb_add(unsigned* p, unsigned v) { return __hip_atomic_fetch_add(p, v, __ATOMIC_RELAXED, __HIP_MEMORY_SCOPE_AGENT); }
; #define XB_SPIN(cond, bar) do { unsigned _sp = 0; while (cond) { __builtin_amdgcn_s_sleep(1); \
;     if ((++_sp & 255u) == 0u) { if (xb_ld(&(bar)[XB_TMO])) break; if (_sp > XB_SPIN_CAP) { atomicAdd(&(bar)[XB_TMO], 1u); break; } } } } while (0)
; __device__ __forceinline__ void xcd_barrier(const XcdBarrier& b) {
;     ...
;         const unsigned old = xb_add(&bar[XB_XSUB(b.x)], 1u);
;         const unsigned gen = old / nloc;
;         if (old + 1u == (gen + 1u) * nloc) {
;             __builtin_amdgcn_fence(__ATOMIC_RELEASE, "agent");
;             asm volatile("s_waitcnt vmcnt(0)" ::: "memory");
;             const unsigned og = xb_add(&bar[XB_TOP], 1u);
;             const unsigned tg = og / nx;
;             if (og + 1u == (tg + 1u) * nx) xb_add(&bar[XB_TOPGEN], 1u);
;             else XB_SPIN(xb_ld(&bar[XB_TOPGEN]) == tg, bar);
;             __builtin_amdgcn_fence(__ATOMIC_ACQUIRE, "agent");
;             xb_add(&bar[XB_XGEN(b.x)], 1u);
;             asm volatile("s_waitcnt vmcnt(0)" ::: "memory");
;         } else {
;             XB_SPIN(xb_ld(&bar[XB_XGEN(b.x)]) == gen, bar);
.LBB0_763:
	s_lshl_b32 s26, s44, 6
	s_add_i32 s84, s26, 0x500
	s_lshl_b64 s[6:7], s[84:85], 2
	s_add_u32 s6, s40, s6
	s_addc_u32 s7, s41, s7
	v_mov_b64_e32 v[4:5], s[6:7]
	v_mov_b32_e32 v3, 1
	buffer_wbl2 sc1
	s_waitcnt vmcnt(0)
	flat_atomic_add v4, v[4:5], v3 sc0
	v_cvt_f32_u32_e32 v3, v2
	v_sub_u32_e32 v5, 0, v2
	v_rcp_iflag_f32_e32 v3, v3
	s_nop 0
	v_mul_f32_e32 v3, 0x4f7ffffe, v3
	v_cvt_u32_f32_e32 v3, v3
	v_mul_lo_u32 v5, v5, v3
	v_mul_hi_u32 v5, v3, v5
	v_add_u32_e32 v3, v3, v5
	s_waitcnt vmcnt(0) lgkmcnt(0)
	v_mul_hi_u32 v3, v4, v3
	v_mul_lo_u32 v5, v3, v2
	v_sub_u32_e32 v5, v4, v5
	v_cmp_ge_u32_e32 vcc, v5, v2
	v_add_u32_e32 v6, 1, v3
	s_nop 0
	v_cndmask_b32_e32 v3, v3, v6, vcc
	v_sub_u32_e32 v6, v5, v2
	v_cndmask_b32_e32 v5, v5, v6, vcc
	v_cmp_ge_u32_e32 vcc, v5, v2
	v_add_u32_e32 v5, 1, v3
	v_add_u32_e32 v6, 1, v4
	v_cndmask_b32_e32 v3, v3, v5, vcc
	v_mad_u64_u32 v[4:5], s[6:7], v2, v3, v[2:3]
	v_cmp_ne_u32_e32 vcc, v6, v4
	s_and_saveexec_b64 s[6:7], vcc
	s_xor_b64 s[6:7], exec, s[6:7]
	s_cbranch_execz .LBB0_776
	s_add_i32 s84, s26, 0x900
	s_lshl_b64 s[8:9], s[84:85], 2
	s_add_u32 s10, s40, s8
	s_addc_u32 s11, s41, s9
	v_mov_b64_e32 v[4:5], s[10:11]
	flat_load_dword v0, v[4:5] sc1
	s_waitcnt vmcnt(0) lgkmcnt(0)
	v_cmp_eq_u32_e32 vcc, v0, v3
	s_and_saveexec_b64 s[8:9], vcc
	s_cbranch_execz .LBB0_775
	s_mov_b32 s27, 1
	s_mov_b64 s[12:13], 0
	s_branch .LBB0_767

; __device__ __forceinline__ unsigned xb_ld(unsigned* p)              { return __hip_atomic_load(p, __ATOMIC_RELAXED, __HIP_MEMORY_SCOPE_AGENT); }
; __device__ __forceinline__ unsigned xb_add(unsigned* p, unsigned v) { return __hip_atomic_fetch_add(p, v, __ATOMIC_RELAXED, __HIP_MEMORY_SCOPE_AGENT); }
; #define XB_SPIN(cond, bar) do { unsigned _sp = 0; while (cond) { __builtin_amdgcn_s_sleep(1); \
;     if ((++_sp & 255u) == 0u) { if (xb_ld(&(bar)[XB_TMO])) break; if (_sp > XB_SPIN_CAP) { atomicAdd(&(bar)[XB_TMO], 1u); break; } } } } while (0)
; __device__ __forceinline__ void xcd_barrier(const XcdBarrier& b) {
;     ...
;             __builtin_amdgcn_fence(__ATOMIC_RELEASE, "agent");
;             asm volatile("s_waitcnt vmcnt(0)" ::: "memory");
;             const unsigned og = xb_add(&bar[XB_TOP], 1u);
;             const unsigned tg = og / nx;
;             if (og + 1u == (tg + 1u) * nx) xb_add(&bar[XB_TOPGEN], 1u);
;             else XB_SPIN(xb_ld(&bar[XB_TOPGEN]) == tg, bar);
.LBB0_776:
	s_andn2_saveexec_b64 s[6:7], s[6:7]
	s_cbranch_execz .LBB0_792
	v_mov_b32_e32 v2, s40
	v_add_co_u32_e32 v2, vcc, 0x3000, v2
	v_mov_b32_e32 v3, s41
	s_nop 1
	v_addc_co_u32_e32 v3, vcc, 0, v3, vcc
	v_mov_b32_e32 v4, 1
	flat_atomic_add v2, v[2:3], v4 offset:1024 sc0
	v_cvt_f32_u32_e32 v3, v0
	v_sub_u32_e32 v4, 0, v0
	s_mov_b64 s[10:11], -1
	v_rcp_iflag_f32_e32 v3, v3
	s_nop 0
	v_mul_f32_e32 v3, 0x4f7ffffe, v3
	v_cvt_u32_f32_e32 v3, v3
	v_mul_lo_u32 v4, v4, v3
	v_mul_hi_u32 v4, v3, v4
	v_add_u32_e32 v3, v3, v4
	s_waitcnt vmcnt(0) lgkmcnt(0)
	v_mul_hi_u32 v3, v2, v3
	v_mul_lo_u32 v4, v3, v0
	v_sub_u32_e32 v4, v2, v4
	v_cmp_ge_u32_e32 vcc, v4, v0
	v_add_u32_e32 v5, 1, v3
	s_nop 0
	v_cndmask_b32_e32 v3, v3, v5, vcc
	v_sub_u32_e32 v5, v4, v0
	v_cndmask_b32_e32 v4, v4, v5, vcc
	v_cmp_ge_u32_e32 vcc, v4, v0
	v_add_u32_e32 v4, 1, v3
	v_add_u32_e32 v5, 1, v2
	v_cndmask_b32_e32 v4, v3, v4, vcc
	v_mad_u64_u32 v[2:3], s[6:7], v0, v4, v[0:1]
	s_add_u32 s6, s40, 0x3500
	s_addc_u32 s7, s41, 0
	v_cmp_ne_u32_e32 vcc, v5, v2
	v_mov_b64_e32 v[2:3], s[6:7]
	s_and_saveexec_b64 s[8:9], vcc
	s_cbranch_execz .LBB0_789
	v_mov_b64_e32 v[2:3], s[6:7]
	flat_load_dword v0, v[2:3] sc1
	s_mov_b64 s[14:15], 0
	s_waitcnt vmcnt(0) lgkmcnt(0)
	v_cmp_eq_u32_e32 vcc, v0, v4
	s_and_saveexec_b64 s[12:13], vcc
	s_cbranch_execz .LBB0_788
	s_add_u32 s10, s40, 0x200
	s_addc_u32 s11, s41, 0
	s_mov_b32 s27, 1
	s_branch .LBB0_781

; __device__ __forceinline__ unsigned xb_ld(unsigned* p)              { return __hip_atomic_load(p, __ATOMIC_RELAXED, __HIP_MEMORY_SCOPE_AGENT); }
; __device__ __forceinline__ unsigned xb_add(unsigned* p, unsigned v) { return __hip_atomic_fetch_add(p, v, __ATOMIC_RELAXED, __HIP_MEMORY_SCOPE_AGENT); }
; #define XB_SPIN(cond, bar) do { unsigned _sp = 0; while (cond) { __builtin_amdgcn_s_sleep(1); \
;     if ((++_sp & 255u) == 0u) { if (xb_ld(&(bar)[XB_TMO])) break; if (_sp > XB_SPIN_CAP) { atomicAdd(&(bar)[XB_TMO], 1u); break; } } } } while (0)
; __device__ __forceinline__ void xcd_barrier(const XcdBarrier& b) {
;     ...
;         const unsigned old = xb_add(&bar[XB_XSUB(b.x)], 1u);
;         const unsigned gen = old / nloc;
;         if (old + 1u == (gen + 1u) * nloc) {
;             __builtin_amdgcn_fence(__ATOMIC_RELEASE, "agent");
;             asm volatile("s_waitcnt vmcnt(0)" ::: "memory");
;             const unsigned og = xb_add(&bar[XB_TOP], 1u);
;             const unsigned tg = og / nx;
;             if (og + 1u == (tg + 1u) * nx) xb_add(&bar[XB_TOPGEN], 1u);
;             else XB_SPIN(xb_ld(&bar[XB_TOPGEN]) == tg, bar);
;             __builtin_amdgcn_fence(__ATOMIC_ACQUIRE, "agent");
;             xb_add(&bar[XB_XGEN(b.x)], 1u);
;             asm volatile("s_waitcnt vmcnt(0)" ::: "memory");
;         } else {
;             XB_SPIN(xb_ld(&bar[XB_XGEN(b.x)]) == gen, bar);
.LBB0_880:
	s_lshl_b32 s26, s33, 6
	s_add_i32 s84, s26, 0x500
	s_lshl_b64 s[6:7], s[84:85], 2
	s_add_u32 s6, s40, s6
	s_addc_u32 s7, s41, s7
	v_mov_b64_e32 v[4:5], s[6:7]
	v_mov_b32_e32 v3, 1
	buffer_wbl2 sc1
	s_waitcnt vmcnt(0)
	flat_atomic_add v4, v[4:5], v3 sc0
	v_cvt_f32_u32_e32 v3, v2
	v_sub_u32_e32 v5, 0, v2
	v_rcp_iflag_f32_e32 v3, v3
	s_nop 0
	v_mul_f32_e32 v3, 0x4f7ffffe, v3
	v_cvt_u32_f32_e32 v3, v3
	v_mul_lo_u32 v5, v5, v3
	v_mul_hi_u32 v5, v3, v5
	v_add_u32_e32 v3, v3, v5
	s_waitcnt vmcnt(0) lgkmcnt(0)
	v_mul_hi_u32 v3, v4, v3
	v_mul_lo_u32 v5, v3, v2
	v_sub_u32_e32 v5, v4, v5
	v_cmp_ge_u32_e32 vcc, v5, v2
	v_add_u32_e32 v6, 1, v3
	s_nop 0
	v_cndmask_b32_e32 v3, v3, v6, vcc
	v_sub_u32_e32 v6, v5, v2
	v_cndmask_b32_e32 v5, v5, v6, vcc
	v_cmp_ge_u32_e32 vcc, v5, v2
	v_add_u32_e32 v5, 1, v3
	v_add_u32_e32 v6, 1, v4
	v_cndmask_b32_e32 v3, v3, v5, vcc
	v_mad_u64_u32 v[4:5], s[6:7], v2, v3, v[2:3]
	v_cmp_ne_u32_e32 vcc, v6, v4
	s_and_saveexec_b64 s[6:7], vcc
	s_xor_b64 s[6:7], exec, s[6:7]
	s_cbranch_execz .LBB0_893
	s_add_i32 s84, s26, 0x900
	s_lshl_b64 s[8:9], s[84:85], 2
	s_add_u32 s10, s40, s8
	s_addc_u32 s11, s41, s9
	v_mov_b64_e32 v[4:5], s[10:11]
	flat_load_dword v0, v[4:5] sc1
	s_waitcnt vmcnt(0) lgkmcnt(0)
	v_cmp_eq_u32_e32 vcc, v0, v3
	s_and_saveexec_b64 s[8:9], vcc
	s_cbranch_execz .LBB0_892
	s_mov_b32 s27, 1
	s_mov_b64 s[12:13], 0
	s_branch .LBB0_884

; __device__ __forceinline__ unsigned xb_ld(unsigned* p)              { return __hip_atomic_load(p, __ATOMIC_RELAXED, __HIP_MEMORY_SCOPE_AGENT); }
; __device__ __forceinline__ unsigned xb_add(unsigned* p, unsigned v) { return __hip_atomic_fetch_add(p, v, __ATOMIC_RELAXED, __HIP_MEMORY_SCOPE_AGENT); }
; #define XB_SPIN(cond, bar) do { unsigned _sp = 0; while (cond) { __builtin_amdgcn_s_sleep(1); \
;     if ((++_sp & 255u) == 0u) { if (xb_ld(&(bar)[XB_TMO])) break; if (_sp > XB_SPIN_CAP) { atomicAdd(&(bar)[XB_TMO], 1u); break; } } } } while (0)
; __device__ __forceinline__ void xcd_barrier(const XcdBarrier& b) {
;     ...
;         const unsigned old = xb_add(&bar[XB_XSUB(b.x)], 1u);
;         const unsigned gen = old / nloc;
;         if (old + 1u == (gen + 1u) * nloc) {
;             __builtin_amdgcn_fence(__ATOMIC_RELEASE, "agent");
;             asm volatile("s_waitcnt vmcnt(0)" ::: "memory");
;             const unsigned og = xb_add(&bar[XB_TOP], 1u);
;             const unsigned tg = og / nx;
;             if (og + 1u == (tg + 1u) * nx) xb_add(&bar[XB_TOPGEN], 1u);
;             else XB_SPIN(xb_ld(&bar[XB_TOPGEN]) == tg, bar);
;             __builtin_amdgcn_fence(__ATOMIC_ACQUIRE, "agent");
;             xb_add(&bar[XB_XGEN(b.x)], 1u);
;             asm volatile("s_waitcnt vmcnt(0)" ::: "memory");
;         } else {
;             XB_SPIN(xb_ld(&bar[XB_XGEN(b.x)]) == gen, bar);
.LBB0_1002:
	s_lshl_b32 s28, s6, 6
	s_add_i32 s84, s28, 0x500
	s_lshl_b64 s[6:7], s[84:85], 2
	s_add_u32 s6, s48, s6
	s_addc_u32 s7, s49, s7
	v_mov_b64_e32 v[4:5], s[6:7]
	v_mov_b32_e32 v3, 1
	buffer_wbl2 sc1
	s_waitcnt vmcnt(0)
	flat_atomic_add v4, v[4:5], v3 sc0
	v_cvt_f32_u32_e32 v3, v2
	v_sub_u32_e32 v5, 0, v2
	v_rcp_iflag_f32_e32 v3, v3
	s_nop 0
	v_mul_f32_e32 v3, 0x4f7ffffe, v3
	v_cvt_u32_f32_e32 v3, v3
	v_mul_lo_u32 v5, v5, v3
	v_mul_hi_u32 v5, v3, v5
	v_add_u32_e32 v3, v3, v5
	s_waitcnt vmcnt(0) lgkmcnt(0)
	v_mul_hi_u32 v3, v4, v3
	v_mul_lo_u32 v5, v3, v2
	v_sub_u32_e32 v5, v4, v5
	v_cmp_ge_u32_e32 vcc, v5, v2
	v_add_u32_e32 v6, 1, v3
	s_nop 0
	v_cndmask_b32_e32 v3, v3, v6, vcc
	v_sub_u32_e32 v6, v5, v2
	v_cndmask_b32_e32 v5, v5, v6, vcc
	v_cmp_ge_u32_e32 vcc, v5, v2
	v_add_u32_e32 v5, 1, v3
	v_add_u32_e32 v6, 1, v4
	v_cndmask_b32_e32 v3, v3, v5, vcc
	v_mad_u64_u32 v[4:5], s[6:7], v2, v3, v[2:3]
	v_cmp_ne_u32_e32 vcc, v6, v4
	s_and_saveexec_b64 s[6:7], vcc
	s_xor_b64 s[8:9], exec, s[6:7]
	s_cbranch_execz .LBB0_1015
	s_add_i32 s84, s28, 0x900
	s_lshl_b64 s[6:7], s[84:85], 2
	s_add_u32 s12, s48, s6
	s_addc_u32 s13, s49, s7
	v_mov_b64_e32 v[4:5], s[12:13]
	flat_load_dword v0, v[4:5] sc1
	s_waitcnt vmcnt(0) lgkmcnt(0)
	v_cmp_eq_u32_e32 vcc, v0, v3
	s_and_saveexec_b64 s[10:11], vcc
	s_cbranch_execz .LBB0_1014
	s_mov_b32 s6, 1
	s_mov_b64 s[14:15], 0
	s_branch .LBB0_1006

; __device__ __forceinline__ unsigned xb_ld(unsigned* p)              { return __hip_atomic_load(p, __ATOMIC_RELAXED, __HIP_MEMORY_SCOPE_AGENT); }
; __device__ __forceinline__ unsigned xb_add(unsigned* p, unsigned v) { return __hip_atomic_fetch_add(p, v, __ATOMIC_RELAXED, __HIP_MEMORY_SCOPE_AGENT); }
; #define XB_SPIN(cond, bar) do { unsigned _sp = 0; while (cond) { __builtin_amdgcn_s_sleep(1); \
;     if ((++_sp & 255u) == 0u) { if (xb_ld(&(bar)[XB_TMO])) break; if (_sp > XB_SPIN_CAP) { atomicAdd(&(bar)[XB_TMO], 1u); break; } } } } while (0)
; __device__ __forceinline__ void xcd_barrier(const XcdBarrier& b) {
;     ...
;             __builtin_amdgcn_fence(__ATOMIC_RELEASE, "agent");
;             asm volatile("s_waitcnt vmcnt(0)" ::: "memory");
;             const unsigned og = xb_add(&bar[XB_TOP], 1u);
;             const unsigned tg = og / nx;
;             if (og + 1u == (tg + 1u) * nx) xb_add(&bar[XB_TOPGEN], 1u);
;             else XB_SPIN(xb_ld(&bar[XB_TOPGEN]) == tg, bar);
.LBB0_1015:
	s_andn2_saveexec_b64 s[6:7], s[8:9]
	s_cbranch_execz .LBB0_1031
	v_mov_b32_e32 v2, s48
	v_add_co_u32_e32 v2, vcc, 0x3000, v2
	v_mov_b32_e32 v3, s49
	s_nop 1
	v_addc_co_u32_e32 v3, vcc, 0, v3, vcc
	v_mov_b32_e32 v4, 1
	flat_atomic_add v2, v[2:3], v4 offset:1024 sc0
	v_cvt_f32_u32_e32 v3, v0
	v_sub_u32_e32 v4, 0, v0
	s_add_u32 s8, s48, 0x3500
	s_addc_u32 s9, s49, 0
	v_rcp_iflag_f32_e32 v3, v3
	s_mov_b64 s[12:13], -1
	v_mul_f32_e32 v3, 0x4f7ffffe, v3
	v_cvt_u32_f32_e32 v3, v3
	v_mul_lo_u32 v4, v4, v3
	v_mul_hi_u32 v4, v3, v4
	v_add_u32_e32 v3, v3, v4
	s_waitcnt vmcnt(0) lgkmcnt(0)
	v_mul_hi_u32 v3, v2, v3
	v_mul_lo_u32 v4, v3, v0
	v_sub_u32_e32 v4, v2, v4
	v_cmp_ge_u32_e32 vcc, v4, v0
	v_add_u32_e32 v5, 1, v3
	s_nop 0
	v_cndmask_b32_e32 v3, v3, v5, vcc
	v_sub_u32_e32 v5, v4, v0
	v_cndmask_b32_e32 v4, v4, v5, vcc
	v_cmp_ge_u32_e32 vcc, v4, v0
	v_add_u32_e32 v4, 1, v3
	v_add_u32_e32 v5, 1, v2
	v_cndmask_b32_e32 v4, v3, v4, vcc
	v_mad_u64_u32 v[2:3], s[6:7], v0, v4, v[0:1]
	v_cmp_ne_u32_e32 vcc, v5, v2
	v_mov_b64_e32 v[2:3], s[8:9]
	s_and_saveexec_b64 s[10:11], vcc
	s_cbranch_execz .LBB0_1028
	v_mov_b64_e32 v[2:3], s[8:9]
	flat_load_dword v0, v[2:3] sc1
	s_mov_b64 s[16:17], 0
	s_waitcnt vmcnt(0) lgkmcnt(0)
	v_cmp_eq_u32_e32 vcc, v0, v4
	s_and_saveexec_b64 s[14:15], vcc
	s_cbranch_execz .LBB0_1027
	s_add_u32 s12, s48, 0x200
	s_addc_u32 s13, s49, 0
	s_mov_b32 s6, 1
	s_branch .LBB0_1020

; __device__ __forceinline__ unsigned xb_ld(unsigned* p)              { return __hip_atomic_load(p, __ATOMIC_RELAXED, __HIP_MEMORY_SCOPE_AGENT); }
; __device__ __forceinline__ unsigned xb_add(unsigned* p, unsigned v) { return __hip_atomic_fetch_add(p, v, __ATOMIC_RELAXED, __HIP_MEMORY_SCOPE_AGENT); }
; #define XB_SPIN(cond, bar) do { unsigned _sp = 0; while (cond) { __builtin_amdgcn_s_sleep(1); \
;     if ((++_sp & 255u) == 0u) { if (xb_ld(&(bar)[XB_TMO])) break; if (_sp > XB_SPIN_CAP) { atomicAdd(&(bar)[XB_TMO], 1u); break; } } } } while (0)
; __device__ __forceinline__ void xcd_barrier(const XcdBarrier& b) {
;     ...
;         const unsigned old = xb_add(&bar[XB_XSUB(b.x)], 1u);
;         const unsigned gen = old / nloc;
;         if (old + 1u == (gen + 1u) * nloc) {
;             __builtin_amdgcn_fence(__ATOMIC_RELEASE, "agent");
;             asm volatile("s_waitcnt vmcnt(0)" ::: "memory");
;             const unsigned og = xb_add(&bar[XB_TOP], 1u);
;             const unsigned tg = og / nx;
;             if (og + 1u == (tg + 1u) * nx) xb_add(&bar[XB_TOPGEN], 1u);
;             else XB_SPIN(xb_ld(&bar[XB_TOPGEN]) == tg, bar);
;             __builtin_amdgcn_fence(__ATOMIC_ACQUIRE, "agent");
;             xb_add(&bar[XB_XGEN(b.x)], 1u);
;             asm volatile("s_waitcnt vmcnt(0)" ::: "memory");
;         } else {
;             XB_SPIN(xb_ld(&bar[XB_XGEN(b.x)]) == gen, bar);
.LBB0_1301:
	s_lshl_b32 s26, s33, 6
	s_add_i32 s84, s26, 0x500
	s_lshl_b64 s[6:7], s[84:85], 2
	s_add_u32 s6, s0, s6
	s_addc_u32 s7, s1, s7
	v_mov_b64_e32 v[4:5], s[6:7]
	v_mov_b32_e32 v3, 1
	buffer_wbl2 sc1
	s_waitcnt vmcnt(0)
	flat_atomic_add v4, v[4:5], v3 sc0
	v_cvt_f32_u32_e32 v3, v2
	v_sub_u32_e32 v5, 0, v2
	v_rcp_iflag_f32_e32 v3, v3
	s_nop 0
	v_mul_f32_e32 v3, 0x4f7ffffe, v3
	v_cvt_u32_f32_e32 v3, v3
	v_mul_lo_u32 v5, v5, v3
	v_mul_hi_u32 v5, v3, v5
	v_add_u32_e32 v3, v3, v5
	s_waitcnt vmcnt(0) lgkmcnt(0)
	v_mul_hi_u32 v3, v4, v3
	v_mul_lo_u32 v5, v3, v2
	v_sub_u32_e32 v5, v4, v5
	v_cmp_ge_u32_e32 vcc, v5, v2
	v_add_u32_e32 v6, 1, v3
	s_nop 0
	v_cndmask_b32_e32 v3, v3, v6, vcc
	v_sub_u32_e32 v6, v5, v2
	v_cndmask_b32_e32 v5, v5, v6, vcc
	v_cmp_ge_u32_e32 vcc, v5, v2
	v_add_u32_e32 v5, 1, v3
	v_add_u32_e32 v6, 1, v4
	v_cndmask_b32_e32 v3, v3, v5, vcc
	v_mad_u64_u32 v[4:5], s[6:7], v2, v3, v[2:3]
	v_cmp_ne_u32_e32 vcc, v6, v4
	s_and_saveexec_b64 s[6:7], vcc
	s_xor_b64 s[6:7], exec, s[6:7]
	s_cbranch_execz .LBB0_1314
	s_add_i32 s84, s26, 0x900
	s_lshl_b64 s[8:9], s[84:85], 2
	s_add_u32 s10, s0, s8
	s_addc_u32 s11, s1, s9
	v_mov_b64_e32 v[4:5], s[10:11]
	flat_load_dword v0, v[4:5] sc1
	s_waitcnt vmcnt(0) lgkmcnt(0)
	v_cmp_eq_u32_e32 vcc, v0, v3
	s_and_saveexec_b64 s[8:9], vcc
	s_cbranch_execz .LBB0_1313
	s_mov_b32 s27, 1
	s_mov_b64 s[12:13], 0
	s_branch .LBB0_1305

; __device__ __forceinline__ unsigned xb_ld(unsigned* p)              { return __hip_atomic_load(p, __ATOMIC_RELAXED, __HIP_MEMORY_SCOPE_AGENT); }
; __device__ __forceinline__ unsigned xb_add(unsigned* p, unsigned v) { return __hip_atomic_fetch_add(p, v, __ATOMIC_RELAXED, __HIP_MEMORY_SCOPE_AGENT); }
; #define XB_SPIN(cond, bar) do { unsigned _sp = 0; while (cond) { __builtin_amdgcn_s_sleep(1); \
;     if ((++_sp & 255u) == 0u) { if (xb_ld(&(bar)[XB_TMO])) break; if (_sp > XB_SPIN_CAP) { atomicAdd(&(bar)[XB_TMO], 1u); break; } } } } while (0)
; __device__ __forceinline__ void xcd_barrier(const XcdBarrier& b) {
;     ...
;             __builtin_amdgcn_fence(__ATOMIC_RELEASE, "agent");
;             asm volatile("s_waitcnt vmcnt(0)" ::: "memory");
;             const unsigned og = xb_add(&bar[XB_TOP], 1u);
;             const unsigned tg = og / nx;
;             if (og + 1u == (tg + 1u) * nx) xb_add(&bar[XB_TOPGEN], 1u);
;             else XB_SPIN(xb_ld(&bar[XB_TOPGEN]) == tg, bar);
.LBB0_1315:
	v_mov_b32_e32 v2, s0
	v_add_co_u32_e32 v2, vcc, 0x3000, v2
	v_mov_b32_e32 v3, s1
	s_nop 1
	v_addc_co_u32_e32 v3, vcc, 0, v3, vcc
	v_mov_b32_e32 v4, 1
	flat_atomic_add v2, v[2:3], v4 offset:1024 sc0
	v_cvt_f32_u32_e32 v3, v0
	v_sub_u32_e32 v4, 0, v0
	s_mov_b64 s[10:11], -1
	v_rcp_iflag_f32_e32 v3, v3
	s_nop 0
	v_mul_f32_e32 v3, 0x4f7ffffe, v3
	v_cvt_u32_f32_e32 v3, v3
	v_mul_lo_u32 v4, v4, v3
	v_mul_hi_u32 v4, v3, v4
	v_add_u32_e32 v3, v3, v4
	s_waitcnt vmcnt(0) lgkmcnt(0)
	v_mul_hi_u32 v3, v2, v3
	v_mul_lo_u32 v4, v3, v0
	v_sub_u32_e32 v4, v2, v4
	v_cmp_ge_u32_e32 vcc, v4, v0
	v_add_u32_e32 v5, 1, v3
	s_nop 0
	v_cndmask_b32_e32 v3, v3, v5, vcc
	v_sub_u32_e32 v5, v4, v0
	v_cndmask_b32_e32 v4, v4, v5, vcc
	v_cmp_ge_u32_e32 vcc, v4, v0
	v_add_u32_e32 v4, 1, v3
	v_add_u32_e32 v5, 1, v2
	v_cndmask_b32_e32 v4, v3, v4, vcc
	v_mad_u64_u32 v[2:3], s[6:7], v0, v4, v[0:1]
	s_add_u32 s6, s0, 0x3500
	s_addc_u32 s7, s1, 0
	v_cmp_ne_u32_e32 vcc, v5, v2
	v_mov_b64_e32 v[2:3], s[6:7]
	s_and_saveexec_b64 s[8:9], vcc
	s_cbranch_execz .LBB0_1327
	v_mov_b64_e32 v[2:3], s[6:7]
	flat_load_dword v0, v[2:3] sc1
	s_mov_b64 s[14:15], 0
	s_waitcnt vmcnt(0) lgkmcnt(0)
	v_cmp_eq_u32_e32 vcc, v0, v4
	s_and_saveexec_b64 s[12:13], vcc
	s_cbranch_execz .LBB0_1326
	s_add_u32 s10, s0, 0x200
	s_addc_u32 s11, s1, 0
	s_mov_b32 s27, 1
	s_branch .LBB0_1319
